# attention sample group rewritten by hand: K and V rows read from LDS once for all 8 tokens (was once per token), scores for 8 tokens accumulated together, f32 VALU math unchanged
# speedup vs baseline: 1.0146x; 1.0146x over previous
.LBB0_693:
	s_or_b64 exec, exec, s[4:5]
	s_add_i32 s4, s17, 1
	v_cvt_f32_u32_e32 v4, s4
	s_waitcnt lgkmcnt(0)
	ds_write_b128 v55, v[0:3]
	s_waitcnt lgkmcnt(0)
	s_barrier
	v_mul_f32_e32 v8, -0.5, v4
	ds_read_b32 v0, v46
	ds_read_b32 v1, v47
	ds_read_b32 v2, v48
	ds_read_b32 v3, v49
	ds_read_b32 v4, v50
	ds_read_b32 v5, v51
	ds_read_b32 v6, v52
	ds_read_b32 v7, v53
	v_exp_f32_e32 v14, v8
	s_lshl_b32 s4, s17, 6
	s_lshl_b32 s30, s4, 1
	v_lshl_add_u64 v[8:9], v[36:37], 0, s[30:31]
	s_mov_b32 s4, 0
	v_mov_b32_e32 v15, s95
	v_mov_b32_e32 v32, v56
	v_mov_b32_e32 v33, v57
	v_add_u32_e32 v34, 0x8800, v58
	v_mov_b32_e32 v176, 0
	v_mov_b32_e32 v177, 0
	v_mov_b32_e32 v178, 0
	v_mov_b32_e32 v179, 0
	v_mov_b32_e32 v180, 0
	v_mov_b32_e32 v181, 0
	v_mov_b32_e32 v182, 0
	v_mov_b32_e32 v183, 0
	v_mov_b32_e32 v184, 0
	v_mov_b32_e32 v185, 0
	v_mov_b32_e32 v186, 0
	v_mov_b32_e32 v187, 0
	v_mov_b32_e32 v188, 0
	v_mov_b32_e32 v189, 0
	v_mov_b32_e32 v190, 0
	v_mov_b32_e32 v191, 0
	v_mov_b32_e32 v192, 0
	v_mov_b32_e32 v193, 0
	v_mov_b32_e32 v194, 0
	v_mov_b32_e32 v195, 0
	v_mov_b32_e32 v196, 0
	v_mov_b32_e32 v197, 0
	v_mov_b32_e32 v198, 0
	v_mov_b32_e32 v199, 0
	ds_read_b128 v[60:63], v32 offset:0
	ds_read_b128 v[64:67], v32 offset:16
	ds_read_b128 v[68:71], v33 offset:0
	ds_read_b128 v[72:75], v33 offset:16
	ds_read_b128 v[76:79], v34 offset:0
	ds_read_b128 v[80:83], v34 offset:16
	ds_read_b128 v[16:19], v15 offset:0
	s_mov_b32 s17, 0
.Lsm_qk:
	ds_read_b128 v[84:87], v32 offset:32
	ds_read_b128 v[88:91], v32 offset:48
	ds_read_b128 v[92:95], v33 offset:32
	ds_read_b128 v[96:99], v33 offset:48
	ds_read_b128 v[100:103], v34 offset:32
	ds_read_b128 v[104:107], v34 offset:48
	ds_read_b128 v[20:23], v15 offset:128
	s_waitcnt lgkmcnt(7)
	v_lshlrev_b32_e32 v24, 16, v16
	v_and_b32_e32 v25, 0xffff0000, v16
	v_lshlrev_b32_e32 v26, 16, v17
	v_and_b32_e32 v27, 0xffff0000, v17
	v_lshlrev_b32_e32 v28, 16, v18
	v_and_b32_e32 v29, 0xffff0000, v18
	v_lshlrev_b32_e32 v30, 16, v19
	v_and_b32_e32 v31, 0xffff0000, v19
	v_fmac_f32_e32 v176, v60, v24
	v_fmac_f32_e32 v177, v68, v24
	v_fmac_f32_e32 v178, v76, v24
	v_fmac_f32_e32 v176, v61, v25
	v_fmac_f32_e32 v177, v69, v25
	v_fmac_f32_e32 v178, v77, v25
	v_fmac_f32_e32 v176, v62, v26
	v_fmac_f32_e32 v177, v70, v26
	v_fmac_f32_e32 v178, v78, v26
	v_fmac_f32_e32 v176, v63, v27
	v_fmac_f32_e32 v177, v71, v27
	v_fmac_f32_e32 v178, v79, v27
	v_fmac_f32_e32 v176, v64, v28
	v_fmac_f32_e32 v177, v72, v28
	v_fmac_f32_e32 v178, v80, v28
	v_fmac_f32_e32 v176, v65, v29
	v_fmac_f32_e32 v177, v73, v29
	v_fmac_f32_e32 v178, v81, v29
	v_fmac_f32_e32 v176, v66, v30
	v_fmac_f32_e32 v177, v74, v30
	v_fmac_f32_e32 v178, v82, v30
	v_fmac_f32_e32 v176, v67, v31
	v_fmac_f32_e32 v177, v75, v31
	v_fmac_f32_e32 v178, v83, v31
	ds_read_b128 v[16:19], v15 offset:256
	s_waitcnt lgkmcnt(1)
	v_lshlrev_b32_e32 v24, 16, v20
	v_and_b32_e32 v25, 0xffff0000, v20
	v_lshlrev_b32_e32 v26, 16, v21
	v_and_b32_e32 v27, 0xffff0000, v21
	v_lshlrev_b32_e32 v28, 16, v22
	v_and_b32_e32 v29, 0xffff0000, v22
	v_lshlrev_b32_e32 v30, 16, v23
	v_and_b32_e32 v31, 0xffff0000, v23
	v_fmac_f32_e32 v179, v60, v24
	v_fmac_f32_e32 v180, v68, v24
	v_fmac_f32_e32 v181, v76, v24
	v_fmac_f32_e32 v179, v61, v25
	v_fmac_f32_e32 v180, v69, v25
	v_fmac_f32_e32 v181, v77, v25
	v_fmac_f32_e32 v179, v62, v26
	v_fmac_f32_e32 v180, v70, v26
	v_fmac_f32_e32 v181, v78, v26
	v_fmac_f32_e32 v179, v63, v27
	v_fmac_f32_e32 v180, v71, v27
	v_fmac_f32_e32 v181, v79, v27
	v_fmac_f32_e32 v179, v64, v28
	v_fmac_f32_e32 v180, v72, v28
	v_fmac_f32_e32 v181, v80, v28
	v_fmac_f32_e32 v179, v65, v29
	v_fmac_f32_e32 v180, v73, v29
	v_fmac_f32_e32 v181, v81, v29
	v_fmac_f32_e32 v179, v66, v30
	v_fmac_f32_e32 v180, v74, v30
	v_fmac_f32_e32 v181, v82, v30
	v_fmac_f32_e32 v179, v67, v31
	v_fmac_f32_e32 v180, v75, v31
	v_fmac_f32_e32 v181, v83, v31
	ds_read_b128 v[20:23], v15 offset:384
	s_waitcnt lgkmcnt(1)
	v_lshlrev_b32_e32 v24, 16, v16
	v_and_b32_e32 v25, 0xffff0000, v16
	v_lshlrev_b32_e32 v26, 16, v17
	v_and_b32_e32 v27, 0xffff0000, v17
	v_lshlrev_b32_e32 v28, 16, v18
	v_and_b32_e32 v29, 0xffff0000, v18
	v_lshlrev_b32_e32 v30, 16, v19
	v_and_b32_e32 v31, 0xffff0000, v19
	v_fmac_f32_e32 v182, v60, v24
	v_fmac_f32_e32 v183, v68, v24
	v_fmac_f32_e32 v184, v76, v24
	v_fmac_f32_e32 v182, v61, v25
	v_fmac_f32_e32 v183, v69, v25
	v_fmac_f32_e32 v184, v77, v25
	v_fmac_f32_e32 v182, v62, v26
	v_fmac_f32_e32 v183, v70, v26
	v_fmac_f32_e32 v184, v78, v26
	v_fmac_f32_e32 v182, v63, v27
	v_fmac_f32_e32 v183, v71, v27
	v_fmac_f32_e32 v184, v79, v27
	v_fmac_f32_e32 v182, v64, v28
	v_fmac_f32_e32 v183, v72, v28
	v_fmac_f32_e32 v184, v80, v28
	v_fmac_f32_e32 v182, v65, v29
	v_fmac_f32_e32 v183, v73, v29
	v_fmac_f32_e32 v184, v81, v29
	v_fmac_f32_e32 v182, v66, v30
	v_fmac_f32_e32 v183, v74, v30
	v_fmac_f32_e32 v184, v82, v30
	v_fmac_f32_e32 v182, v67, v31
	v_fmac_f32_e32 v183, v75, v31
	v_fmac_f32_e32 v184, v83, v31
	ds_read_b128 v[16:19], v15 offset:512
	s_waitcnt lgkmcnt(1)
	v_lshlrev_b32_e32 v24, 16, v20
	v_and_b32_e32 v25, 0xffff0000, v20
	v_lshlrev_b32_e32 v26, 16, v21
	v_and_b32_e32 v27, 0xffff0000, v21
	v_lshlrev_b32_e32 v28, 16, v22
	v_and_b32_e32 v29, 0xffff0000, v22
	v_lshlrev_b32_e32 v30, 16, v23
	v_and_b32_e32 v31, 0xffff0000, v23
	v_fmac_f32_e32 v185, v60, v24
	v_fmac_f32_e32 v186, v68, v24
	v_fmac_f32_e32 v187, v76, v24
	v_fmac_f32_e32 v185, v61, v25
	v_fmac_f32_e32 v186, v69, v25
	v_fmac_f32_e32 v187, v77, v25
	v_fmac_f32_e32 v185, v62, v26
	v_fmac_f32_e32 v186, v70, v26
	v_fmac_f32_e32 v187, v78, v26
	v_fmac_f32_e32 v185, v63, v27
	v_fmac_f32_e32 v186, v71, v27
	v_fmac_f32_e32 v187, v79, v27
	v_fmac_f32_e32 v185, v64, v28
	v_fmac_f32_e32 v186, v72, v28
	v_fmac_f32_e32 v187, v80, v28
	v_fmac_f32_e32 v185, v65, v29
	v_fmac_f32_e32 v186, v73, v29
	v_fmac_f32_e32 v187, v81, v29
	v_fmac_f32_e32 v185, v66, v30
	v_fmac_f32_e32 v186, v74, v30
	v_fmac_f32_e32 v187, v82, v30
	v_fmac_f32_e32 v185, v67, v31
	v_fmac_f32_e32 v186, v75, v31
	v_fmac_f32_e32 v187, v83, v31
	ds_read_b128 v[20:23], v15 offset:640
	s_waitcnt lgkmcnt(1)
	v_lshlrev_b32_e32 v24, 16, v16
	v_and_b32_e32 v25, 0xffff0000, v16
	v_lshlrev_b32_e32 v26, 16, v17
	v_and_b32_e32 v27, 0xffff0000, v17
	v_lshlrev_b32_e32 v28, 16, v18
	v_and_b32_e32 v29, 0xffff0000, v18
	v_lshlrev_b32_e32 v30, 16, v19
	v_and_b32_e32 v31, 0xffff0000, v19
	v_fmac_f32_e32 v188, v60, v24
	v_fmac_f32_e32 v189, v68, v24
	v_fmac_f32_e32 v190, v76, v24
	v_fmac_f32_e32 v188, v61, v25
	v_fmac_f32_e32 v189, v69, v25
	v_fmac_f32_e32 v190, v77, v25
	v_fmac_f32_e32 v188, v62, v26
	v_fmac_f32_e32 v189, v70, v26
	v_fmac_f32_e32 v190, v78, v26
	v_fmac_f32_e32 v188, v63, v27
	v_fmac_f32_e32 v189, v71, v27
	v_fmac_f32_e32 v190, v79, v27
	v_fmac_f32_e32 v188, v64, v28
	v_fmac_f32_e32 v189, v72, v28
	v_fmac_f32_e32 v190, v80, v28
	v_fmac_f32_e32 v188, v65, v29
	v_fmac_f32_e32 v189, v73, v29
	v_fmac_f32_e32 v190, v81, v29
	v_fmac_f32_e32 v188, v66, v30
	v_fmac_f32_e32 v189, v74, v30
	v_fmac_f32_e32 v190, v82, v30
	v_fmac_f32_e32 v188, v67, v31
	v_fmac_f32_e32 v189, v75, v31
	v_fmac_f32_e32 v190, v83, v31
	ds_read_b128 v[16:19], v15 offset:768
	s_waitcnt lgkmcnt(1)
	v_lshlrev_b32_e32 v24, 16, v20
	v_and_b32_e32 v25, 0xffff0000, v20
	v_lshlrev_b32_e32 v26, 16, v21
	v_and_b32_e32 v27, 0xffff0000, v21
	v_lshlrev_b32_e32 v28, 16, v22
	v_and_b32_e32 v29, 0xffff0000, v22
	v_lshlrev_b32_e32 v30, 16, v23
	v_and_b32_e32 v31, 0xffff0000, v23
	v_fmac_f32_e32 v191, v60, v24
	v_fmac_f32_e32 v192, v68, v24
	v_fmac_f32_e32 v193, v76, v24
	v_fmac_f32_e32 v191, v61, v25
	v_fmac_f32_e32 v192, v69, v25
	v_fmac_f32_e32 v193, v77, v25
	v_fmac_f32_e32 v191, v62, v26
	v_fmac_f32_e32 v192, v70, v26
	v_fmac_f32_e32 v193, v78, v26
	v_fmac_f32_e32 v191, v63, v27
	v_fmac_f32_e32 v192, v71, v27
	v_fmac_f32_e32 v193, v79, v27
	v_fmac_f32_e32 v191, v64, v28
	v_fmac_f32_e32 v192, v72, v28
	v_fmac_f32_e32 v193, v80, v28
	v_fmac_f32_e32 v191, v65, v29
	v_fmac_f32_e32 v192, v73, v29
	v_fmac_f32_e32 v193, v81, v29
	v_fmac_f32_e32 v191, v66, v30
	v_fmac_f32_e32 v192, v74, v30
	v_fmac_f32_e32 v193, v82, v30
	v_fmac_f32_e32 v191, v67, v31
	v_fmac_f32_e32 v192, v75, v31
	v_fmac_f32_e32 v193, v83, v31
	ds_read_b128 v[20:23], v15 offset:896
	s_waitcnt lgkmcnt(1)
	v_lshlrev_b32_e32 v24, 16, v16
	v_and_b32_e32 v25, 0xffff0000, v16
	v_lshlrev_b32_e32 v26, 16, v17
	v_and_b32_e32 v27, 0xffff0000, v17
	v_lshlrev_b32_e32 v28, 16, v18
	v_and_b32_e32 v29, 0xffff0000, v18
	v_lshlrev_b32_e32 v30, 16, v19
	v_and_b32_e32 v31, 0xffff0000, v19
	v_fmac_f32_e32 v194, v60, v24
	v_fmac_f32_e32 v195, v68, v24
	v_fmac_f32_e32 v196, v76, v24
	v_fmac_f32_e32 v194, v61, v25
	v_fmac_f32_e32 v195, v69, v25
	v_fmac_f32_e32 v196, v77, v25
	v_fmac_f32_e32 v194, v62, v26
	v_fmac_f32_e32 v195, v70, v26
	v_fmac_f32_e32 v196, v78, v26
	v_fmac_f32_e32 v194, v63, v27
	v_fmac_f32_e32 v195, v71, v27
	v_fmac_f32_e32 v196, v79, v27
	v_fmac_f32_e32 v194, v64, v28
	v_fmac_f32_e32 v195, v72, v28
	v_fmac_f32_e32 v196, v80, v28
	v_fmac_f32_e32 v194, v65, v29
	v_fmac_f32_e32 v195, v73, v29
	v_fmac_f32_e32 v196, v81, v29
	v_fmac_f32_e32 v194, v66, v30
	v_fmac_f32_e32 v195, v74, v30
	v_fmac_f32_e32 v196, v82, v30
	v_fmac_f32_e32 v194, v67, v31
	v_fmac_f32_e32 v195, v75, v31
	v_fmac_f32_e32 v196, v83, v31
	ds_read_b128 v[16:19], v15 offset:16
	s_waitcnt lgkmcnt(1)
	v_lshlrev_b32_e32 v24, 16, v20
	v_and_b32_e32 v25, 0xffff0000, v20
	v_lshlrev_b32_e32 v26, 16, v21
	v_and_b32_e32 v27, 0xffff0000, v21
	v_lshlrev_b32_e32 v28, 16, v22
	v_and_b32_e32 v29, 0xffff0000, v22
	v_lshlrev_b32_e32 v30, 16, v23
	v_and_b32_e32 v31, 0xffff0000, v23
	v_fmac_f32_e32 v197, v60, v24
	v_fmac_f32_e32 v198, v68, v24
	v_fmac_f32_e32 v199, v76, v24
	v_fmac_f32_e32 v197, v61, v25
	v_fmac_f32_e32 v198, v69, v25
	v_fmac_f32_e32 v199, v77, v25
	v_fmac_f32_e32 v197, v62, v26
	v_fmac_f32_e32 v198, v70, v26
	v_fmac_f32_e32 v199, v78, v26
	v_fmac_f32_e32 v197, v63, v27
	v_fmac_f32_e32 v198, v71, v27
	v_fmac_f32_e32 v199, v79, v27
	v_fmac_f32_e32 v197, v64, v28
	v_fmac_f32_e32 v198, v72, v28
	v_fmac_f32_e32 v199, v80, v28
	v_fmac_f32_e32 v197, v65, v29
	v_fmac_f32_e32 v198, v73, v29
	v_fmac_f32_e32 v199, v81, v29
	v_fmac_f32_e32 v197, v66, v30
	v_fmac_f32_e32 v198, v74, v30
	v_fmac_f32_e32 v199, v82, v30
	v_fmac_f32_e32 v197, v67, v31
	v_fmac_f32_e32 v198, v75, v31
	v_fmac_f32_e32 v199, v83, v31
	ds_read_b128 v[60:63], v32 offset:64
	ds_read_b128 v[64:67], v32 offset:80
	ds_read_b128 v[68:71], v33 offset:64
	ds_read_b128 v[72:75], v33 offset:80
	ds_read_b128 v[76:79], v34 offset:64
	ds_read_b128 v[80:83], v34 offset:80
	ds_read_b128 v[20:23], v15 offset:144
	s_waitcnt lgkmcnt(7)
	v_lshlrev_b32_e32 v24, 16, v16
	v_and_b32_e32 v25, 0xffff0000, v16
	v_lshlrev_b32_e32 v26, 16, v17
	v_and_b32_e32 v27, 0xffff0000, v17
	v_lshlrev_b32_e32 v28, 16, v18
	v_and_b32_e32 v29, 0xffff0000, v18
	v_lshlrev_b32_e32 v30, 16, v19
	v_and_b32_e32 v31, 0xffff0000, v19
	v_fmac_f32_e32 v176, v84, v24
	v_fmac_f32_e32 v177, v92, v24
	v_fmac_f32_e32 v178, v100, v24
	v_fmac_f32_e32 v176, v85, v25
	v_fmac_f32_e32 v177, v93, v25
	v_fmac_f32_e32 v178, v101, v25
	v_fmac_f32_e32 v176, v86, v26
	v_fmac_f32_e32 v177, v94, v26
	v_fmac_f32_e32 v178, v102, v26
	v_fmac_f32_e32 v176, v87, v27
	v_fmac_f32_e32 v177, v95, v27
	v_fmac_f32_e32 v178, v103, v27
	v_fmac_f32_e32 v176, v88, v28
	v_fmac_f32_e32 v177, v96, v28
	v_fmac_f32_e32 v178, v104, v28
	v_fmac_f32_e32 v176, v89, v29
	v_fmac_f32_e32 v177, v97, v29
	v_fmac_f32_e32 v178, v105, v29
	v_fmac_f32_e32 v176, v90, v30
	v_fmac_f32_e32 v177, v98, v30
	v_fmac_f32_e32 v178, v106, v30
	v_fmac_f32_e32 v176, v91, v31
	v_fmac_f32_e32 v177, v99, v31
	v_fmac_f32_e32 v178, v107, v31
	ds_read_b128 v[16:19], v15 offset:272
	s_waitcnt lgkmcnt(1)
	v_lshlrev_b32_e32 v24, 16, v20
	v_and_b32_e32 v25, 0xffff0000, v20
	v_lshlrev_b32_e32 v26, 16, v21
	v_and_b32_e32 v27, 0xffff0000, v21
	v_lshlrev_b32_e32 v28, 16, v22
	v_and_b32_e32 v29, 0xffff0000, v22
	v_lshlrev_b32_e32 v30, 16, v23
	v_and_b32_e32 v31, 0xffff0000, v23
	v_fmac_f32_e32 v179, v84, v24
	v_fmac_f32_e32 v180, v92, v24
	v_fmac_f32_e32 v181, v100, v24
	v_fmac_f32_e32 v179, v85, v25
	v_fmac_f32_e32 v180, v93, v25
	v_fmac_f32_e32 v181, v101, v25
	v_fmac_f32_e32 v179, v86, v26
	v_fmac_f32_e32 v180, v94, v26
	v_fmac_f32_e32 v181, v102, v26
	v_fmac_f32_e32 v179, v87, v27
	v_fmac_f32_e32 v180, v95, v27
	v_fmac_f32_e32 v181, v103, v27
	v_fmac_f32_e32 v179, v88, v28
	v_fmac_f32_e32 v180, v96, v28
	v_fmac_f32_e32 v181, v104, v28
	v_fmac_f32_e32 v179, v89, v29
	v_fmac_f32_e32 v180, v97, v29
	v_fmac_f32_e32 v181, v105, v29
	v_fmac_f32_e32 v179, v90, v30
	v_fmac_f32_e32 v180, v98, v30
	v_fmac_f32_e32 v181, v106, v30
	v_fmac_f32_e32 v179, v91, v31
	v_fmac_f32_e32 v180, v99, v31
	v_fmac_f32_e32 v181, v107, v31
	ds_read_b128 v[20:23], v15 offset:400
	s_waitcnt lgkmcnt(1)
	v_lshlrev_b32_e32 v24, 16, v16
	v_and_b32_e32 v25, 0xffff0000, v16
	v_lshlrev_b32_e32 v26, 16, v17
	v_and_b32_e32 v27, 0xffff0000, v17
	v_lshlrev_b32_e32 v28, 16, v18
	v_and_b32_e32 v29, 0xffff0000, v18
	v_lshlrev_b32_e32 v30, 16, v19
	v_and_b32_e32 v31, 0xffff0000, v19
	v_fmac_f32_e32 v182, v84, v24
	v_fmac_f32_e32 v183, v92, v24
	v_fmac_f32_e32 v184, v100, v24
	v_fmac_f32_e32 v182, v85, v25
	v_fmac_f32_e32 v183, v93, v25
	v_fmac_f32_e32 v184, v101, v25
	v_fmac_f32_e32 v182, v86, v26
	v_fmac_f32_e32 v183, v94, v26
	v_fmac_f32_e32 v184, v102, v26
	v_fmac_f32_e32 v182, v87, v27
	v_fmac_f32_e32 v183, v95, v27
	v_fmac_f32_e32 v184, v103, v27
	v_fmac_f32_e32 v182, v88, v28
	v_fmac_f32_e32 v183, v96, v28
	v_fmac_f32_e32 v184, v104, v28
	v_fmac_f32_e32 v182, v89, v29
	v_fmac_f32_e32 v183, v97, v29
	v_fmac_f32_e32 v184, v105, v29
	v_fmac_f32_e32 v182, v90, v30
	v_fmac_f32_e32 v183, v98, v30
	v_fmac_f32_e32 v184, v106, v30
	v_fmac_f32_e32 v182, v91, v31
	v_fmac_f32_e32 v183, v99, v31
	v_fmac_f32_e32 v184, v107, v31
	ds_read_b128 v[16:19], v15 offset:528
	s_waitcnt lgkmcnt(1)
	v_lshlrev_b32_e32 v24, 16, v20
	v_and_b32_e32 v25, 0xffff0000, v20
	v_lshlrev_b32_e32 v26, 16, v21
	v_and_b32_e32 v27, 0xffff0000, v21
	v_lshlrev_b32_e32 v28, 16, v22
	v_and_b32_e32 v29, 0xffff0000, v22
	v_lshlrev_b32_e32 v30, 16, v23
	v_and_b32_e32 v31, 0xffff0000, v23
	v_fmac_f32_e32 v185, v84, v24
	v_fmac_f32_e32 v186, v92, v24
	v_fmac_f32_e32 v187, v100, v24
	v_fmac_f32_e32 v185, v85, v25
	v_fmac_f32_e32 v186, v93, v25
	v_fmac_f32_e32 v187, v101, v25
	v_fmac_f32_e32 v185, v86, v26
	v_fmac_f32_e32 v186, v94, v26
	v_fmac_f32_e32 v187, v102, v26
	v_fmac_f32_e32 v185, v87, v27
	v_fmac_f32_e32 v186, v95, v27
	v_fmac_f32_e32 v187, v103, v27
	v_fmac_f32_e32 v185, v88, v28
	v_fmac_f32_e32 v186, v96, v28
	v_fmac_f32_e32 v187, v104, v28
	v_fmac_f32_e32 v185, v89, v29
	v_fmac_f32_e32 v186, v97, v29
	v_fmac_f32_e32 v187, v105, v29
	v_fmac_f32_e32 v185, v90, v30
	v_fmac_f32_e32 v186, v98, v30
	v_fmac_f32_e32 v187, v106, v30
	v_fmac_f32_e32 v185, v91, v31
	v_fmac_f32_e32 v186, v99, v31
	v_fmac_f32_e32 v187, v107, v31
	ds_read_b128 v[20:23], v15 offset:656
	s_waitcnt lgkmcnt(1)
	v_lshlrev_b32_e32 v24, 16, v16
	v_and_b32_e32 v25, 0xffff0000, v16
	v_lshlrev_b32_e32 v26, 16, v17
	v_and_b32_e32 v27, 0xffff0000, v17
	v_lshlrev_b32_e32 v28, 16, v18
	v_and_b32_e32 v29, 0xffff0000, v18
	v_lshlrev_b32_e32 v30, 16, v19
	v_and_b32_e32 v31, 0xffff0000, v19
	v_fmac_f32_e32 v188, v84, v24
	v_fmac_f32_e32 v189, v92, v24
	v_fmac_f32_e32 v190, v100, v24
	v_fmac_f32_e32 v188, v85, v25
	v_fmac_f32_e32 v189, v93, v25
	v_fmac_f32_e32 v190, v101, v25
	v_fmac_f32_e32 v188, v86, v26
	v_fmac_f32_e32 v189, v94, v26
	v_fmac_f32_e32 v190, v102, v26
	v_fmac_f32_e32 v188, v87, v27
	v_fmac_f32_e32 v189, v95, v27
	v_fmac_f32_e32 v190, v103, v27
	v_fmac_f32_e32 v188, v88, v28
	v_fmac_f32_e32 v189, v96, v28
	v_fmac_f32_e32 v190, v104, v28
	v_fmac_f32_e32 v188, v89, v29
	v_fmac_f32_e32 v189, v97, v29
	v_fmac_f32_e32 v190, v105, v29
	v_fmac_f32_e32 v188, v90, v30
	v_fmac_f32_e32 v189, v98, v30
	v_fmac_f32_e32 v190, v106, v30
	v_fmac_f32_e32 v188, v91, v31
	v_fmac_f32_e32 v189, v99, v31
	v_fmac_f32_e32 v190, v107, v31
	ds_read_b128 v[16:19], v15 offset:784
	s_waitcnt lgkmcnt(1)
	v_lshlrev_b32_e32 v24, 16, v20
	v_and_b32_e32 v25, 0xffff0000, v20
	v_lshlrev_b32_e32 v26, 16, v21
	v_and_b32_e32 v27, 0xffff0000, v21
	v_lshlrev_b32_e32 v28, 16, v22
	v_and_b32_e32 v29, 0xffff0000, v22
	v_lshlrev_b32_e32 v30, 16, v23
	v_and_b32_e32 v31, 0xffff0000, v23
	v_fmac_f32_e32 v191, v84, v24
	v_fmac_f32_e32 v192, v92, v24
	v_fmac_f32_e32 v193, v100, v24
	v_fmac_f32_e32 v191, v85, v25
	v_fmac_f32_e32 v192, v93, v25
	v_fmac_f32_e32 v193, v101, v25
	v_fmac_f32_e32 v191, v86, v26
	v_fmac_f32_e32 v192, v94, v26
	v_fmac_f32_e32 v193, v102, v26
	v_fmac_f32_e32 v191, v87, v27
	v_fmac_f32_e32 v192, v95, v27
	v_fmac_f32_e32 v193, v103, v27
	v_fmac_f32_e32 v191, v88, v28
	v_fmac_f32_e32 v192, v96, v28
	v_fmac_f32_e32 v193, v104, v28
	v_fmac_f32_e32 v191, v89, v29
	v_fmac_f32_e32 v192, v97, v29
	v_fmac_f32_e32 v193, v105, v29
	v_fmac_f32_e32 v191, v90, v30
	v_fmac_f32_e32 v192, v98, v30
	v_fmac_f32_e32 v193, v106, v30
	v_fmac_f32_e32 v191, v91, v31
	v_fmac_f32_e32 v192, v99, v31
	v_fmac_f32_e32 v193, v107, v31
	ds_read_b128 v[20:23], v15 offset:912
	s_waitcnt lgkmcnt(1)
	v_lshlrev_b32_e32 v24, 16, v16
	v_and_b32_e32 v25, 0xffff0000, v16
	v_lshlrev_b32_e32 v26, 16, v17
	v_and_b32_e32 v27, 0xffff0000, v17
	v_lshlrev_b32_e32 v28, 16, v18
	v_and_b32_e32 v29, 0xffff0000, v18
	v_lshlrev_b32_e32 v30, 16, v19
	v_and_b32_e32 v31, 0xffff0000, v19
	v_fmac_f32_e32 v194, v84, v24
	v_fmac_f32_e32 v195, v92, v24
	v_fmac_f32_e32 v196, v100, v24
	v_fmac_f32_e32 v194, v85, v25
	v_fmac_f32_e32 v195, v93, v25
	v_fmac_f32_e32 v196, v101, v25
	v_fmac_f32_e32 v194, v86, v26
	v_fmac_f32_e32 v195, v94, v26
	v_fmac_f32_e32 v196, v102, v26
	v_fmac_f32_e32 v194, v87, v27
	v_fmac_f32_e32 v195, v95, v27
	v_fmac_f32_e32 v196, v103, v27
	v_fmac_f32_e32 v194, v88, v28
	v_fmac_f32_e32 v195, v96, v28
	v_fmac_f32_e32 v196, v104, v28
	v_fmac_f32_e32 v194, v89, v29
	v_fmac_f32_e32 v195, v97, v29
	v_fmac_f32_e32 v196, v105, v29
	v_fmac_f32_e32 v194, v90, v30
	v_fmac_f32_e32 v195, v98, v30
	v_fmac_f32_e32 v196, v106, v30
	v_fmac_f32_e32 v194, v91, v31
	v_fmac_f32_e32 v195, v99, v31
	v_fmac_f32_e32 v196, v107, v31
	ds_read_b128 v[16:19], v15 offset:32
	s_waitcnt lgkmcnt(1)
	v_lshlrev_b32_e32 v24, 16, v20
	v_and_b32_e32 v25, 0xffff0000, v20
	v_lshlrev_b32_e32 v26, 16, v21
	v_and_b32_e32 v27, 0xffff0000, v21
	v_lshlrev_b32_e32 v28, 16, v22
	v_and_b32_e32 v29, 0xffff0000, v22
	v_lshlrev_b32_e32 v30, 16, v23
	v_and_b32_e32 v31, 0xffff0000, v23
	v_fmac_f32_e32 v197, v84, v24
	v_fmac_f32_e32 v198, v92, v24
	v_fmac_f32_e32 v199, v100, v24
	v_fmac_f32_e32 v197, v85, v25
	v_fmac_f32_e32 v198, v93, v25
	v_fmac_f32_e32 v199, v101, v25
	v_fmac_f32_e32 v197, v86, v26
	v_fmac_f32_e32 v198, v94, v26
	v_fmac_f32_e32 v199, v102, v26
	v_fmac_f32_e32 v197, v87, v27
	v_fmac_f32_e32 v198, v95, v27
	v_fmac_f32_e32 v199, v103, v27
	v_fmac_f32_e32 v197, v88, v28
	v_fmac_f32_e32 v198, v96, v28
	v_fmac_f32_e32 v199, v104, v28
	v_fmac_f32_e32 v197, v89, v29
	v_fmac_f32_e32 v198, v97, v29
	v_fmac_f32_e32 v199, v105, v29
	v_fmac_f32_e32 v197, v90, v30
	v_fmac_f32_e32 v198, v98, v30
	v_fmac_f32_e32 v199, v106, v30
	v_fmac_f32_e32 v197, v91, v31
	v_fmac_f32_e32 v198, v99, v31
	v_fmac_f32_e32 v199, v107, v31
	v_add_u32_e32 v32, 64, v32
	v_add_u32_e32 v33, 64, v33
	v_add_u32_e32 v34, 64, v34
	v_add_u32_e32 v15, 32, v15
	s_add_i32 s17, s17, 1
	s_cmp_lt_u32 s17, 4
	s_cbranch_scc1 .Lsm_qk
	s_waitcnt lgkmcnt(0)
	v_sub_u32_e32 v10, s3, v108
	v_add_u32_e32 v38, 0, v10
	v_cvt_f32_i32_e32 v39, v38
	v_cmp_gt_u32_e32 vcc, s3, v38
	v_mul_f32_e32 v39, v14, v39
	v_fma_f32 v176, v176, s52, -v39
	v_cndmask_b32_e32 v176, v241, v176, vcc
	v_add_u32_e32 v38, 0xffffffc0, v10
	v_cvt_f32_i32_e32 v39, v38
	v_cmp_gt_u32_e32 vcc, s3, v38
	v_mul_f32_e32 v39, v14, v39
	v_fma_f32 v177, v177, s52, -v39
	v_cndmask_b32_e32 v177, v241, v177, vcc
	v_add_u32_e32 v38, 0xffffff80, v10
	v_cvt_f32_i32_e32 v39, v38
	v_cmp_gt_u32_e32 vcc, s3, v38
	v_mul_f32_e32 v39, v14, v39
	v_fma_f32 v178, v178, s52, -v39
	s_and_b64 vcc, s[40:41], vcc
	v_cndmask_b32_e32 v178, v241, v178, vcc
	v_max3_f32 v40, v176, v177, v178
	v_mov_b32_e32 v41, v241
	s_nop 1
	v_mov_b32_dpp v41, v40 quad_perm:[1,0,3,2] row_mask:0xf bank_mask:0xf
	v_max_f32_e32 v40, v40, v41
	v_mov_b32_e32 v41, v241
	s_nop 1
	v_mov_b32_dpp v41, v40 quad_perm:[2,3,0,1] row_mask:0xf bank_mask:0xf
	v_max_f32_e32 v40, v40, v41
	v_mov_b32_e32 v41, v241
	s_nop 1
	v_mov_b32_dpp v41, v40 row_half_mirror row_mask:0xf bank_mask:0xf
	v_max_f32_e32 v40, v40, v41
	v_mov_b32_e32 v41, v241
	s_nop 1
	v_mov_b32_dpp v41, v40 row_mirror row_mask:0xf bank_mask:0xf
	v_max_f32_e32 v40, v40, v41
	v_mov_b32_e32 v41, v241
	s_nop 1
	v_mov_b32_dpp v41, v40 row_bcast:15 row_mask:0xa bank_mask:0xf
	v_max_f32_e32 v40, v40, v41
	v_mov_b32_e32 v41, v241
	s_nop 1
	v_mov_b32_dpp v41, v40 row_bcast:31 row_mask:0xc bank_mask:0xf
	v_max_f32_e32 v40, v40, v41
	s_nop 0
	v_readlane_b32 s4, v40, 63
	s_nop 1
	v_max_f32_e32 v42, s4, v59
	v_sub_f32_e32 v176, v176, v42
	v_mul_f32_e32 v176, 0x3fb8aa3b, v176
	v_sub_f32_e32 v177, v177, v42
	v_mul_f32_e32 v177, 0x3fb8aa3b, v177
	v_sub_f32_e32 v178, v178, v42
	v_mul_f32_e32 v178, 0x3fb8aa3b, v178
	v_exp_f32_e32 v176, v176
	v_exp_f32_e32 v177, v177
	v_exp_f32_e32 v178, v178
	v_add_f32_e32 v43, v176, v177
	v_sub_f32_e32 v38, v59, v42
	v_add_f32_e32 v43, v43, v178
	v_mul_f32_e32 v38, 0x3fb8aa3b, v38
	v_exp_f32_e32 v38, v38
	s_nop 1
	v_add_f32_dpp v43, v43, v43 quad_perm:[1,0,3,2] row_mask:0xf bank_mask:0xf bound_ctrl:1
	s_nop 1
	v_add_f32_dpp v43, v43, v43 quad_perm:[2,3,0,1] row_mask:0xf bank_mask:0xf bound_ctrl:1
	s_nop 1
	v_add_f32_dpp v43, v43, v43 row_half_mirror row_mask:0xf bank_mask:0xf bound_ctrl:1
	s_nop 1
	v_add_f32_dpp v43, v43, v43 row_mirror row_mask:0xf bank_mask:0xf bound_ctrl:1
	v_mov_b32_e32 v41, 0
	s_nop 1
	v_mov_b32_dpp v41, v43 row_bcast:15 row_mask:0xa bank_mask:0xf
	v_add_f32_e32 v43, v43, v41
	v_mov_b32_e32 v41, 0
	s_nop 1
	v_mov_b32_dpp v41, v43 row_bcast:31 row_mask:0xc bank_mask:0xf
	v_add_f32_e32 v43, v43, v41
	s_nop 0
	v_readlane_b32 s5, v43, 63
	s_nop 1
	v_add_f32_e32 v200, s5, v38
	v_add_u32_e32 v38, 1, v10
	v_cvt_f32_i32_e32 v39, v38
	v_cmp_gt_u32_e32 vcc, s3, v38
	v_mul_f32_e32 v39, v14, v39
	v_fma_f32 v179, v179, s52, -v39
	v_cndmask_b32_e32 v179, v241, v179, vcc
	v_add_u32_e32 v38, 0xffffffc1, v10
	v_cvt_f32_i32_e32 v39, v38
	v_cmp_gt_u32_e32 vcc, s3, v38
	v_mul_f32_e32 v39, v14, v39
	v_fma_f32 v180, v180, s52, -v39
	v_cndmask_b32_e32 v180, v241, v180, vcc
	v_add_u32_e32 v38, 0xffffff81, v10
	v_cvt_f32_i32_e32 v39, v38
	v_cmp_gt_u32_e32 vcc, s3, v38
	v_mul_f32_e32 v39, v14, v39
	v_fma_f32 v181, v181, s52, -v39
	s_and_b64 vcc, s[40:41], vcc
	v_cndmask_b32_e32 v181, v241, v181, vcc
	v_max3_f32 v40, v179, v180, v181
	v_mov_b32_e32 v41, v241
	s_nop 1
	v_mov_b32_dpp v41, v40 quad_perm:[1,0,3,2] row_mask:0xf bank_mask:0xf
	v_max_f32_e32 v40, v40, v41
	v_mov_b32_e32 v41, v241
	s_nop 1
	v_mov_b32_dpp v41, v40 quad_perm:[2,3,0,1] row_mask:0xf bank_mask:0xf
	v_max_f32_e32 v40, v40, v41
	v_mov_b32_e32 v41, v241
	s_nop 1
	v_mov_b32_dpp v41, v40 row_half_mirror row_mask:0xf bank_mask:0xf
	v_max_f32_e32 v40, v40, v41
	v_mov_b32_e32 v41, v241
	s_nop 1
	v_mov_b32_dpp v41, v40 row_mirror row_mask:0xf bank_mask:0xf
	v_max_f32_e32 v40, v40, v41
	v_mov_b32_e32 v41, v241
	s_nop 1
	v_mov_b32_dpp v41, v40 row_bcast:15 row_mask:0xa bank_mask:0xf
	v_max_f32_e32 v40, v40, v41
	v_mov_b32_e32 v41, v241
	s_nop 1
	v_mov_b32_dpp v41, v40 row_bcast:31 row_mask:0xc bank_mask:0xf
	v_max_f32_e32 v40, v40, v41
	s_nop 0
	v_readlane_b32 s4, v40, 63
	s_nop 1
	v_max_f32_e32 v42, s4, v59
	v_sub_f32_e32 v179, v179, v42
	v_mul_f32_e32 v179, 0x3fb8aa3b, v179
	v_sub_f32_e32 v180, v180, v42
	v_mul_f32_e32 v180, 0x3fb8aa3b, v180
	v_sub_f32_e32 v181, v181, v42
	v_mul_f32_e32 v181, 0x3fb8aa3b, v181
	v_exp_f32_e32 v179, v179
	v_exp_f32_e32 v180, v180
	v_exp_f32_e32 v181, v181
	v_add_f32_e32 v43, v179, v180
	v_sub_f32_e32 v38, v59, v42
	v_add_f32_e32 v43, v43, v181
	v_mul_f32_e32 v38, 0x3fb8aa3b, v38
	v_exp_f32_e32 v38, v38
	s_nop 1
	v_add_f32_dpp v43, v43, v43 quad_perm:[1,0,3,2] row_mask:0xf bank_mask:0xf bound_ctrl:1
	s_nop 1
	v_add_f32_dpp v43, v43, v43 quad_perm:[2,3,0,1] row_mask:0xf bank_mask:0xf bound_ctrl:1
	s_nop 1
	v_add_f32_dpp v43, v43, v43 row_half_mirror row_mask:0xf bank_mask:0xf bound_ctrl:1
	s_nop 1
	v_add_f32_dpp v43, v43, v43 row_mirror row_mask:0xf bank_mask:0xf bound_ctrl:1
	v_mov_b32_e32 v41, 0
	s_nop 1
	v_mov_b32_dpp v41, v43 row_bcast:15 row_mask:0xa bank_mask:0xf
	v_add_f32_e32 v43, v43, v41
	v_mov_b32_e32 v41, 0
	s_nop 1
	v_mov_b32_dpp v41, v43 row_bcast:31 row_mask:0xc bank_mask:0xf
	v_add_f32_e32 v43, v43, v41
	s_nop 0
	v_readlane_b32 s5, v43, 63
	s_nop 1
	v_add_f32_e32 v201, s5, v38
	v_add_u32_e32 v38, 2, v10
	v_cvt_f32_i32_e32 v39, v38
	v_cmp_gt_u32_e32 vcc, s3, v38
	v_mul_f32_e32 v39, v14, v39
	v_fma_f32 v182, v182, s52, -v39
	v_cndmask_b32_e32 v182, v241, v182, vcc
	v_add_u32_e32 v38, 0xffffffc2, v10
	v_cvt_f32_i32_e32 v39, v38
	v_cmp_gt_u32_e32 vcc, s3, v38
	v_mul_f32_e32 v39, v14, v39
	v_fma_f32 v183, v183, s52, -v39
	v_cndmask_b32_e32 v183, v241, v183, vcc
	v_add_u32_e32 v38, 0xffffff82, v10
	v_cvt_f32_i32_e32 v39, v38
	v_cmp_gt_u32_e32 vcc, s3, v38
	v_mul_f32_e32 v39, v14, v39
	v_fma_f32 v184, v184, s52, -v39
	s_and_b64 vcc, s[40:41], vcc
	v_cndmask_b32_e32 v184, v241, v184, vcc
	v_max3_f32 v40, v182, v183, v184
	v_mov_b32_e32 v41, v241
	s_nop 1
	v_mov_b32_dpp v41, v40 quad_perm:[1,0,3,2] row_mask:0xf bank_mask:0xf
	v_max_f32_e32 v40, v40, v41
	v_mov_b32_e32 v41, v241
	s_nop 1
	v_mov_b32_dpp v41, v40 quad_perm:[2,3,0,1] row_mask:0xf bank_mask:0xf
	v_max_f32_e32 v40, v40, v41
	v_mov_b32_e32 v41, v241
	s_nop 1
	v_mov_b32_dpp v41, v40 row_half_mirror row_mask:0xf bank_mask:0xf
	v_max_f32_e32 v40, v40, v41
	v_mov_b32_e32 v41, v241
	s_nop 1
	v_mov_b32_dpp v41, v40 row_mirror row_mask:0xf bank_mask:0xf
	v_max_f32_e32 v40, v40, v41
	v_mov_b32_e32 v41, v241
	s_nop 1
	v_mov_b32_dpp v41, v40 row_bcast:15 row_mask:0xa bank_mask:0xf
	v_max_f32_e32 v40, v40, v41
	v_mov_b32_e32 v41, v241
	s_nop 1
	v_mov_b32_dpp v41, v40 row_bcast:31 row_mask:0xc bank_mask:0xf
	v_max_f32_e32 v40, v40, v41
	s_nop 0
	v_readlane_b32 s4, v40, 63
	s_nop 1
	v_max_f32_e32 v42, s4, v59
	v_sub_f32_e32 v182, v182, v42
	v_mul_f32_e32 v182, 0x3fb8aa3b, v182
	v_sub_f32_e32 v183, v183, v42
	v_mul_f32_e32 v183, 0x3fb8aa3b, v183
	v_sub_f32_e32 v184, v184, v42
	v_mul_f32_e32 v184, 0x3fb8aa3b, v184
	v_exp_f32_e32 v182, v182
	v_exp_f32_e32 v183, v183
	v_exp_f32_e32 v184, v184
	v_add_f32_e32 v43, v182, v183
	v_sub_f32_e32 v38, v59, v42
	v_add_f32_e32 v43, v43, v184
	v_mul_f32_e32 v38, 0x3fb8aa3b, v38
	v_exp_f32_e32 v38, v38
	s_nop 1
	v_add_f32_dpp v43, v43, v43 quad_perm:[1,0,3,2] row_mask:0xf bank_mask:0xf bound_ctrl:1
	s_nop 1
	v_add_f32_dpp v43, v43, v43 quad_perm:[2,3,0,1] row_mask:0xf bank_mask:0xf bound_ctrl:1
	s_nop 1
	v_add_f32_dpp v43, v43, v43 row_half_mirror row_mask:0xf bank_mask:0xf bound_ctrl:1
	s_nop 1
	v_add_f32_dpp v43, v43, v43 row_mirror row_mask:0xf bank_mask:0xf bound_ctrl:1
	v_mov_b32_e32 v41, 0
	s_nop 1
	v_mov_b32_dpp v41, v43 row_bcast:15 row_mask:0xa bank_mask:0xf
	v_add_f32_e32 v43, v43, v41
	v_mov_b32_e32 v41, 0
	s_nop 1
	v_mov_b32_dpp v41, v43 row_bcast:31 row_mask:0xc bank_mask:0xf
	v_add_f32_e32 v43, v43, v41
	s_nop 0
	v_readlane_b32 s5, v43, 63
	s_nop 1
	v_add_f32_e32 v202, s5, v38
	v_add_u32_e32 v38, 3, v10
	v_cvt_f32_i32_e32 v39, v38
	v_cmp_gt_u32_e32 vcc, s3, v38
	v_mul_f32_e32 v39, v14, v39
	v_fma_f32 v185, v185, s52, -v39
	v_cndmask_b32_e32 v185, v241, v185, vcc
	v_add_u32_e32 v38, 0xffffffc3, v10
	v_cvt_f32_i32_e32 v39, v38
	v_cmp_gt_u32_e32 vcc, s3, v38
	v_mul_f32_e32 v39, v14, v39
	v_fma_f32 v186, v186, s52, -v39
	v_cndmask_b32_e32 v186, v241, v186, vcc
	v_add_u32_e32 v38, 0xffffff83, v10
	v_cvt_f32_i32_e32 v39, v38
	v_cmp_gt_u32_e32 vcc, s3, v38
	v_mul_f32_e32 v39, v14, v39
	v_fma_f32 v187, v187, s52, -v39
	s_and_b64 vcc, s[40:41], vcc
	v_cndmask_b32_e32 v187, v241, v187, vcc
	v_max3_f32 v40, v185, v186, v187
	v_mov_b32_e32 v41, v241
	s_nop 1
	v_mov_b32_dpp v41, v40 quad_perm:[1,0,3,2] row_mask:0xf bank_mask:0xf
	v_max_f32_e32 v40, v40, v41
	v_mov_b32_e32 v41, v241
	s_nop 1
	v_mov_b32_dpp v41, v40 quad_perm:[2,3,0,1] row_mask:0xf bank_mask:0xf
	v_max_f32_e32 v40, v40, v41
	v_mov_b32_e32 v41, v241
	s_nop 1
	v_mov_b32_dpp v41, v40 row_half_mirror row_mask:0xf bank_mask:0xf
	v_max_f32_e32 v40, v40, v41
	v_mov_b32_e32 v41, v241
	s_nop 1
	v_mov_b32_dpp v41, v40 row_mirror row_mask:0xf bank_mask:0xf
	v_max_f32_e32 v40, v40, v41
	v_mov_b32_e32 v41, v241
	s_nop 1
	v_mov_b32_dpp v41, v40 row_bcast:15 row_mask:0xa bank_mask:0xf
	v_max_f32_e32 v40, v40, v41
	v_mov_b32_e32 v41, v241
	s_nop 1
	v_mov_b32_dpp v41, v40 row_bcast:31 row_mask:0xc bank_mask:0xf
	v_max_f32_e32 v40, v40, v41
	s_nop 0
	v_readlane_b32 s4, v40, 63
	s_nop 1
	v_max_f32_e32 v42, s4, v59
	v_sub_f32_e32 v185, v185, v42
	v_mul_f32_e32 v185, 0x3fb8aa3b, v185
	v_sub_f32_e32 v186, v186, v42
	v_mul_f32_e32 v186, 0x3fb8aa3b, v186
	v_sub_f32_e32 v187, v187, v42
	v_mul_f32_e32 v187, 0x3fb8aa3b, v187
	v_exp_f32_e32 v185, v185
	v_exp_f32_e32 v186, v186
	v_exp_f32_e32 v187, v187
	v_add_f32_e32 v43, v185, v186
	v_sub_f32_e32 v38, v59, v42
	v_add_f32_e32 v43, v43, v187
	v_mul_f32_e32 v38, 0x3fb8aa3b, v38
	v_exp_f32_e32 v38, v38
	s_nop 1
	v_add_f32_dpp v43, v43, v43 quad_perm:[1,0,3,2] row_mask:0xf bank_mask:0xf bound_ctrl:1
	s_nop 1
	v_add_f32_dpp v43, v43, v43 quad_perm:[2,3,0,1] row_mask:0xf bank_mask:0xf bound_ctrl:1
	s_nop 1
	v_add_f32_dpp v43, v43, v43 row_half_mirror row_mask:0xf bank_mask:0xf bound_ctrl:1
	s_nop 1
	v_add_f32_dpp v43, v43, v43 row_mirror row_mask:0xf bank_mask:0xf bound_ctrl:1
	v_mov_b32_e32 v41, 0
	s_nop 1
	v_mov_b32_dpp v41, v43 row_bcast:15 row_mask:0xa bank_mask:0xf
	v_add_f32_e32 v43, v43, v41
	v_mov_b32_e32 v41, 0
	s_nop 1
	v_mov_b32_dpp v41, v43 row_bcast:31 row_mask:0xc bank_mask:0xf
	v_add_f32_e32 v43, v43, v41
	s_nop 0
	v_readlane_b32 s5, v43, 63
	s_nop 1
	v_add_f32_e32 v203, s5, v38
	v_add_u32_e32 v38, 4, v10
	v_cvt_f32_i32_e32 v39, v38
	v_cmp_gt_u32_e32 vcc, s3, v38
	v_mul_f32_e32 v39, v14, v39
	v_fma_f32 v188, v188, s52, -v39
	v_cndmask_b32_e32 v188, v241, v188, vcc
	v_add_u32_e32 v38, 0xffffffc4, v10
	v_cvt_f32_i32_e32 v39, v38
	v_cmp_gt_u32_e32 vcc, s3, v38
	v_mul_f32_e32 v39, v14, v39
	v_fma_f32 v189, v189, s52, -v39
	v_cndmask_b32_e32 v189, v241, v189, vcc
	v_add_u32_e32 v38, 0xffffff84, v10
	v_cvt_f32_i32_e32 v39, v38
	v_cmp_gt_u32_e32 vcc, s3, v38
	v_mul_f32_e32 v39, v14, v39
	v_fma_f32 v190, v190, s52, -v39
	s_and_b64 vcc, s[40:41], vcc
	v_cndmask_b32_e32 v190, v241, v190, vcc
	v_max3_f32 v40, v188, v189, v190
	v_mov_b32_e32 v41, v241
	s_nop 1
	v_mov_b32_dpp v41, v40 quad_perm:[1,0,3,2] row_mask:0xf bank_mask:0xf
	v_max_f32_e32 v40, v40, v41
	v_mov_b32_e32 v41, v241
	s_nop 1
	v_mov_b32_dpp v41, v40 quad_perm:[2,3,0,1] row_mask:0xf bank_mask:0xf
	v_max_f32_e32 v40, v40, v41
	v_mov_b32_e32 v41, v241
	s_nop 1
	v_mov_b32_dpp v41, v40 row_half_mirror row_mask:0xf bank_mask:0xf
	v_max_f32_e32 v40, v40, v41
	v_mov_b32_e32 v41, v241
	s_nop 1
	v_mov_b32_dpp v41, v40 row_mirror row_mask:0xf bank_mask:0xf
	v_max_f32_e32 v40, v40, v41
	v_mov_b32_e32 v41, v241
	s_nop 1
	v_mov_b32_dpp v41, v40 row_bcast:15 row_mask:0xa bank_mask:0xf
	v_max_f32_e32 v40, v40, v41
	v_mov_b32_e32 v41, v241
	s_nop 1
	v_mov_b32_dpp v41, v40 row_bcast:31 row_mask:0xc bank_mask:0xf
	v_max_f32_e32 v40, v40, v41
	s_nop 0
	v_readlane_b32 s4, v40, 63
	s_nop 1
	v_max_f32_e32 v42, s4, v59
	v_sub_f32_e32 v188, v188, v42
	v_mul_f32_e32 v188, 0x3fb8aa3b, v188
	v_sub_f32_e32 v189, v189, v42
	v_mul_f32_e32 v189, 0x3fb8aa3b, v189
	v_sub_f32_e32 v190, v190, v42
	v_mul_f32_e32 v190, 0x3fb8aa3b, v190
	v_exp_f32_e32 v188, v188
	v_exp_f32_e32 v189, v189
	v_exp_f32_e32 v190, v190
	v_add_f32_e32 v43, v188, v189
	v_sub_f32_e32 v38, v59, v42
	v_add_f32_e32 v43, v43, v190
	v_mul_f32_e32 v38, 0x3fb8aa3b, v38
	v_exp_f32_e32 v38, v38
	s_nop 1
	v_add_f32_dpp v43, v43, v43 quad_perm:[1,0,3,2] row_mask:0xf bank_mask:0xf bound_ctrl:1
	s_nop 1
	v_add_f32_dpp v43, v43, v43 quad_perm:[2,3,0,1] row_mask:0xf bank_mask:0xf bound_ctrl:1
	s_nop 1
	v_add_f32_dpp v43, v43, v43 row_half_mirror row_mask:0xf bank_mask:0xf bound_ctrl:1
	s_nop 1
	v_add_f32_dpp v43, v43, v43 row_mirror row_mask:0xf bank_mask:0xf bound_ctrl:1
	v_mov_b32_e32 v41, 0
	s_nop 1
	v_mov_b32_dpp v41, v43 row_bcast:15 row_mask:0xa bank_mask:0xf
	v_add_f32_e32 v43, v43, v41
	v_mov_b32_e32 v41, 0
	s_nop 1
	v_mov_b32_dpp v41, v43 row_bcast:31 row_mask:0xc bank_mask:0xf
	v_add_f32_e32 v43, v43, v41
	s_nop 0
	v_readlane_b32 s5, v43, 63
	s_nop 1
	v_add_f32_e32 v204, s5, v38
	v_add_u32_e32 v38, 5, v10
	v_cvt_f32_i32_e32 v39, v38
	v_cmp_gt_u32_e32 vcc, s3, v38
	v_mul_f32_e32 v39, v14, v39
	v_fma_f32 v191, v191, s52, -v39
	v_cndmask_b32_e32 v191, v241, v191, vcc
	v_add_u32_e32 v38, 0xffffffc5, v10
	v_cvt_f32_i32_e32 v39, v38
	v_cmp_gt_u32_e32 vcc, s3, v38
	v_mul_f32_e32 v39, v14, v39
	v_fma_f32 v192, v192, s52, -v39
	v_cndmask_b32_e32 v192, v241, v192, vcc
	v_add_u32_e32 v38, 0xffffff85, v10
	v_cvt_f32_i32_e32 v39, v38
	v_cmp_gt_u32_e32 vcc, s3, v38
	v_mul_f32_e32 v39, v14, v39
	v_fma_f32 v193, v193, s52, -v39
	s_and_b64 vcc, s[40:41], vcc
	v_cndmask_b32_e32 v193, v241, v193, vcc
	v_max3_f32 v40, v191, v192, v193
	v_mov_b32_e32 v41, v241
	s_nop 1
	v_mov_b32_dpp v41, v40 quad_perm:[1,0,3,2] row_mask:0xf bank_mask:0xf
	v_max_f32_e32 v40, v40, v41
	v_mov_b32_e32 v41, v241
	s_nop 1
	v_mov_b32_dpp v41, v40 quad_perm:[2,3,0,1] row_mask:0xf bank_mask:0xf
	v_max_f32_e32 v40, v40, v41
	v_mov_b32_e32 v41, v241
	s_nop 1
	v_mov_b32_dpp v41, v40 row_half_mirror row_mask:0xf bank_mask:0xf
	v_max_f32_e32 v40, v40, v41
	v_mov_b32_e32 v41, v241
	s_nop 1
	v_mov_b32_dpp v41, v40 row_mirror row_mask:0xf bank_mask:0xf
	v_max_f32_e32 v40, v40, v41
	v_mov_b32_e32 v41, v241
	s_nop 1
	v_mov_b32_dpp v41, v40 row_bcast:15 row_mask:0xa bank_mask:0xf
	v_max_f32_e32 v40, v40, v41
	v_mov_b32_e32 v41, v241
	s_nop 1
	v_mov_b32_dpp v41, v40 row_bcast:31 row_mask:0xc bank_mask:0xf
	v_max_f32_e32 v40, v40, v41
	s_nop 0
	v_readlane_b32 s4, v40, 63
	s_nop 1
	v_max_f32_e32 v42, s4, v59
	v_sub_f32_e32 v191, v191, v42
	v_mul_f32_e32 v191, 0x3fb8aa3b, v191
	v_sub_f32_e32 v192, v192, v42
	v_mul_f32_e32 v192, 0x3fb8aa3b, v192
	v_sub_f32_e32 v193, v193, v42
	v_mul_f32_e32 v193, 0x3fb8aa3b, v193
	v_exp_f32_e32 v191, v191
	v_exp_f32_e32 v192, v192
	v_exp_f32_e32 v193, v193
	v_add_f32_e32 v43, v191, v192
	v_sub_f32_e32 v38, v59, v42
	v_add_f32_e32 v43, v43, v193
	v_mul_f32_e32 v38, 0x3fb8aa3b, v38
	v_exp_f32_e32 v38, v38
	s_nop 1
	v_add_f32_dpp v43, v43, v43 quad_perm:[1,0,3,2] row_mask:0xf bank_mask:0xf bound_ctrl:1
	s_nop 1
	v_add_f32_dpp v43, v43, v43 quad_perm:[2,3,0,1] row_mask:0xf bank_mask:0xf bound_ctrl:1
	s_nop 1
	v_add_f32_dpp v43, v43, v43 row_half_mirror row_mask:0xf bank_mask:0xf bound_ctrl:1
	s_nop 1
	v_add_f32_dpp v43, v43, v43 row_mirror row_mask:0xf bank_mask:0xf bound_ctrl:1
	v_mov_b32_e32 v41, 0
	s_nop 1
	v_mov_b32_dpp v41, v43 row_bcast:15 row_mask:0xa bank_mask:0xf
	v_add_f32_e32 v43, v43, v41
	v_mov_b32_e32 v41, 0
	s_nop 1
	v_mov_b32_dpp v41, v43 row_bcast:31 row_mask:0xc bank_mask:0xf
	v_add_f32_e32 v43, v43, v41
	s_nop 0
	v_readlane_b32 s5, v43, 63
	s_nop 1
	v_add_f32_e32 v205, s5, v38
	v_add_u32_e32 v38, 6, v10
	v_cvt_f32_i32_e32 v39, v38
	v_cmp_gt_u32_e32 vcc, s3, v38
	v_mul_f32_e32 v39, v14, v39
	v_fma_f32 v194, v194, s52, -v39
	v_cndmask_b32_e32 v194, v241, v194, vcc
	v_add_u32_e32 v38, 0xffffffc6, v10
	v_cvt_f32_i32_e32 v39, v38
	v_cmp_gt_u32_e32 vcc, s3, v38
	v_mul_f32_e32 v39, v14, v39
	v_fma_f32 v195, v195, s52, -v39
	v_cndmask_b32_e32 v195, v241, v195, vcc
	v_add_u32_e32 v38, 0xffffff86, v10
	v_cvt_f32_i32_e32 v39, v38
	v_cmp_gt_u32_e32 vcc, s3, v38
	v_mul_f32_e32 v39, v14, v39
	v_fma_f32 v196, v196, s52, -v39
	s_and_b64 vcc, s[40:41], vcc
	v_cndmask_b32_e32 v196, v241, v196, vcc
	v_max3_f32 v40, v194, v195, v196
	v_mov_b32_e32 v41, v241
	s_nop 1
	v_mov_b32_dpp v41, v40 quad_perm:[1,0,3,2] row_mask:0xf bank_mask:0xf
	v_max_f32_e32 v40, v40, v41
	v_mov_b32_e32 v41, v241
	s_nop 1
	v_mov_b32_dpp v41, v40 quad_perm:[2,3,0,1] row_mask:0xf bank_mask:0xf
	v_max_f32_e32 v40, v40, v41
	v_mov_b32_e32 v41, v241
	s_nop 1
	v_mov_b32_dpp v41, v40 row_half_mirror row_mask:0xf bank_mask:0xf
	v_max_f32_e32 v40, v40, v41
	v_mov_b32_e32 v41, v241
	s_nop 1
	v_mov_b32_dpp v41, v40 row_mirror row_mask:0xf bank_mask:0xf
	v_max_f32_e32 v40, v40, v41
	v_mov_b32_e32 v41, v241
	s_nop 1
	v_mov_b32_dpp v41, v40 row_bcast:15 row_mask:0xa bank_mask:0xf
	v_max_f32_e32 v40, v40, v41
	v_mov_b32_e32 v41, v241
	s_nop 1
	v_mov_b32_dpp v41, v40 row_bcast:31 row_mask:0xc bank_mask:0xf
	v_max_f32_e32 v40, v40, v41
	s_nop 0
	v_readlane_b32 s4, v40, 63
	s_nop 1
	v_max_f32_e32 v42, s4, v59
	v_sub_f32_e32 v194, v194, v42
	v_mul_f32_e32 v194, 0x3fb8aa3b, v194
	v_sub_f32_e32 v195, v195, v42
	v_mul_f32_e32 v195, 0x3fb8aa3b, v195
	v_sub_f32_e32 v196, v196, v42
	v_mul_f32_e32 v196, 0x3fb8aa3b, v196
	v_exp_f32_e32 v194, v194
	v_exp_f32_e32 v195, v195
	v_exp_f32_e32 v196, v196
	v_add_f32_e32 v43, v194, v195
	v_sub_f32_e32 v38, v59, v42
	v_add_f32_e32 v43, v43, v196
	v_mul_f32_e32 v38, 0x3fb8aa3b, v38
	v_exp_f32_e32 v38, v38
	s_nop 1
	v_add_f32_dpp v43, v43, v43 quad_perm:[1,0,3,2] row_mask:0xf bank_mask:0xf bound_ctrl:1
	s_nop 1
	v_add_f32_dpp v43, v43, v43 quad_perm:[2,3,0,1] row_mask:0xf bank_mask:0xf bound_ctrl:1
	s_nop 1
	v_add_f32_dpp v43, v43, v43 row_half_mirror row_mask:0xf bank_mask:0xf bound_ctrl:1
	s_nop 1
	v_add_f32_dpp v43, v43, v43 row_mirror row_mask:0xf bank_mask:0xf bound_ctrl:1
	v_mov_b32_e32 v41, 0
	s_nop 1
	v_mov_b32_dpp v41, v43 row_bcast:15 row_mask:0xa bank_mask:0xf
	v_add_f32_e32 v43, v43, v41
	v_mov_b32_e32 v41, 0
	s_nop 1
	v_mov_b32_dpp v41, v43 row_bcast:31 row_mask:0xc bank_mask:0xf
	v_add_f32_e32 v43, v43, v41
	s_nop 0
	v_readlane_b32 s5, v43, 63
	s_nop 1
	v_add_f32_e32 v206, s5, v38
	v_add_u32_e32 v38, 7, v10
	v_cvt_f32_i32_e32 v39, v38
	v_cmp_gt_u32_e32 vcc, s3, v38
	v_mul_f32_e32 v39, v14, v39
	v_fma_f32 v197, v197, s52, -v39
	v_cndmask_b32_e32 v197, v241, v197, vcc
	v_add_u32_e32 v38, 0xffffffc7, v10
	v_cvt_f32_i32_e32 v39, v38
	v_cmp_gt_u32_e32 vcc, s3, v38
	v_mul_f32_e32 v39, v14, v39
	v_fma_f32 v198, v198, s52, -v39
	v_cndmask_b32_e32 v198, v241, v198, vcc
	v_add_u32_e32 v38, 0xffffff87, v10
	v_cvt_f32_i32_e32 v39, v38
	v_cmp_gt_u32_e32 vcc, s3, v38
	v_mul_f32_e32 v39, v14, v39
	v_fma_f32 v199, v199, s52, -v39
	s_and_b64 vcc, s[40:41], vcc
	v_cndmask_b32_e32 v199, v241, v199, vcc
	v_max3_f32 v40, v197, v198, v199
	v_mov_b32_e32 v41, v241
	s_nop 1
	v_mov_b32_dpp v41, v40 quad_perm:[1,0,3,2] row_mask:0xf bank_mask:0xf
	v_max_f32_e32 v40, v40, v41
	v_mov_b32_e32 v41, v241
	s_nop 1
	v_mov_b32_dpp v41, v40 quad_perm:[2,3,0,1] row_mask:0xf bank_mask:0xf
	v_max_f32_e32 v40, v40, v41
	v_mov_b32_e32 v41, v241
	s_nop 1
	v_mov_b32_dpp v41, v40 row_half_mirror row_mask:0xf bank_mask:0xf
	v_max_f32_e32 v40, v40, v41
	v_mov_b32_e32 v41, v241
	s_nop 1
	v_mov_b32_dpp v41, v40 row_mirror row_mask:0xf bank_mask:0xf
	v_max_f32_e32 v40, v40, v41
	v_mov_b32_e32 v41, v241
	s_nop 1
	v_mov_b32_dpp v41, v40 row_bcast:15 row_mask:0xa bank_mask:0xf
	v_max_f32_e32 v40, v40, v41
	v_mov_b32_e32 v41, v241
	s_nop 1
	v_mov_b32_dpp v41, v40 row_bcast:31 row_mask:0xc bank_mask:0xf
	v_max_f32_e32 v40, v40, v41
	s_nop 0
	v_readlane_b32 s4, v40, 63
	s_nop 1
	v_max_f32_e32 v42, s4, v59
	v_sub_f32_e32 v197, v197, v42
	v_mul_f32_e32 v197, 0x3fb8aa3b, v197
	v_sub_f32_e32 v198, v198, v42
	v_mul_f32_e32 v198, 0x3fb8aa3b, v198
	v_sub_f32_e32 v199, v199, v42
	v_mul_f32_e32 v199, 0x3fb8aa3b, v199
	v_exp_f32_e32 v197, v197
	v_exp_f32_e32 v198, v198
	v_exp_f32_e32 v199, v199
	v_add_f32_e32 v43, v197, v198
	v_sub_f32_e32 v38, v59, v42
	v_add_f32_e32 v43, v43, v199
	v_mul_f32_e32 v38, 0x3fb8aa3b, v38
	v_exp_f32_e32 v38, v38
	s_nop 1
	v_add_f32_dpp v43, v43, v43 quad_perm:[1,0,3,2] row_mask:0xf bank_mask:0xf bound_ctrl:1
	s_nop 1
	v_add_f32_dpp v43, v43, v43 quad_perm:[2,3,0,1] row_mask:0xf bank_mask:0xf bound_ctrl:1
	s_nop 1
	v_add_f32_dpp v43, v43, v43 row_half_mirror row_mask:0xf bank_mask:0xf bound_ctrl:1
	s_nop 1
	v_add_f32_dpp v43, v43, v43 row_mirror row_mask:0xf bank_mask:0xf bound_ctrl:1
	v_mov_b32_e32 v41, 0
	s_nop 1
	v_mov_b32_dpp v41, v43 row_bcast:15 row_mask:0xa bank_mask:0xf
	v_add_f32_e32 v43, v43, v41
	v_mov_b32_e32 v41, 0
	s_nop 1
	v_mov_b32_dpp v41, v43 row_bcast:31 row_mask:0xc bank_mask:0xf
	v_add_f32_e32 v43, v43, v41
	s_nop 0
	v_readlane_b32 s5, v43, 63
	s_nop 1
	v_add_f32_e32 v207, s5, v38
	v_mov_b32_e32 v208, 0
	v_mov_b32_e32 v209, 0
	v_mov_b32_e32 v210, 0
	v_mov_b32_e32 v211, 0
	v_mov_b32_e32 v212, 0
	v_mov_b32_e32 v213, 0
	v_mov_b32_e32 v214, 0
	v_mov_b32_e32 v215, 0
	v_mov_b32_e32 v35, v54
	ds_read2st64_b32 v[216:217], v35 offset0:0 offset1:64
	ds_read2st64_b32 v[218:219], v35 offset0:1 offset1:65
	ds_read2st64_b32 v[220:221], v35 offset0:2 offset1:66
	ds_read2st64_b32 v[222:223], v35 offset0:3 offset1:67
	s_mov_b32 s17, 0
.Lsm_pv:
	ds_read2st64_b32 v[224:225], v35 offset0:4 offset1:68
	ds_read2st64_b32 v[226:227], v35 offset0:5 offset1:69
	ds_read2st64_b32 v[228:229], v35 offset0:6 offset1:70
	ds_read2st64_b32 v[230:231], v35 offset0:7 offset1:71
	s_waitcnt lgkmcnt(4)
	s_add_i32 s30, s17, 0
	s_nop 0
	v_readlane_b32 s4, v176, s30
	v_readlane_b32 s5, v177, s30
	v_readlane_b32 s26, v179, s30
	v_readlane_b32 s27, v180, s30
	v_readlane_b32 s44, v182, s30
	v_readlane_b32 s45, v183, s30
	v_readlane_b32 s46, v185, s30
	v_readlane_b32 s47, v186, s30
	v_fmac_f32_e32 v208, s4, v216
	v_fmac_f32_e32 v208, s5, v217
	v_fmac_f32_e32 v209, s26, v216
	v_fmac_f32_e32 v209, s27, v217
	v_fmac_f32_e32 v210, s44, v216
	v_fmac_f32_e32 v210, s45, v217
	v_fmac_f32_e32 v211, s46, v216
	v_fmac_f32_e32 v211, s47, v217
	v_readlane_b32 s4, v188, s30
	v_readlane_b32 s5, v189, s30
	v_readlane_b32 s26, v191, s30
	v_readlane_b32 s27, v192, s30
	v_readlane_b32 s44, v194, s30
	v_readlane_b32 s45, v195, s30
	v_readlane_b32 s46, v197, s30
	v_readlane_b32 s47, v198, s30
	v_fmac_f32_e32 v212, s4, v216
	v_fmac_f32_e32 v212, s5, v217
	v_fmac_f32_e32 v213, s26, v216
	v_fmac_f32_e32 v213, s27, v217
	v_fmac_f32_e32 v214, s44, v216
	v_fmac_f32_e32 v214, s45, v217
	v_fmac_f32_e32 v215, s46, v216
	v_fmac_f32_e32 v215, s47, v217
	s_add_i32 s30, s17, 1
	s_nop 0
	v_readlane_b32 s4, v176, s30
	v_readlane_b32 s5, v177, s30
	v_readlane_b32 s26, v179, s30
	v_readlane_b32 s27, v180, s30
	v_readlane_b32 s44, v182, s30
	v_readlane_b32 s45, v183, s30
	v_readlane_b32 s46, v185, s30
	v_readlane_b32 s47, v186, s30
	v_fmac_f32_e32 v208, s4, v218
	v_fmac_f32_e32 v208, s5, v219
	v_fmac_f32_e32 v209, s26, v218
	v_fmac_f32_e32 v209, s27, v219
	v_fmac_f32_e32 v210, s44, v218
	v_fmac_f32_e32 v210, s45, v219
	v_fmac_f32_e32 v211, s46, v218
	v_fmac_f32_e32 v211, s47, v219
	v_readlane_b32 s4, v188, s30
	v_readlane_b32 s5, v189, s30
	v_readlane_b32 s26, v191, s30
	v_readlane_b32 s27, v192, s30
	v_readlane_b32 s44, v194, s30
	v_readlane_b32 s45, v195, s30
	v_readlane_b32 s46, v197, s30
	v_readlane_b32 s47, v198, s30
	v_fmac_f32_e32 v212, s4, v218
	v_fmac_f32_e32 v212, s5, v219
	v_fmac_f32_e32 v213, s26, v218
	v_fmac_f32_e32 v213, s27, v219
	v_fmac_f32_e32 v214, s44, v218
	v_fmac_f32_e32 v214, s45, v219
	v_fmac_f32_e32 v215, s46, v218
	v_fmac_f32_e32 v215, s47, v219
	s_add_i32 s30, s17, 2
	s_nop 0
	v_readlane_b32 s4, v176, s30
	v_readlane_b32 s5, v177, s30
	v_readlane_b32 s26, v179, s30
	v_readlane_b32 s27, v180, s30
	v_readlane_b32 s44, v182, s30
	v_readlane_b32 s45, v183, s30
	v_readlane_b32 s46, v185, s30
	v_readlane_b32 s47, v186, s30
	v_fmac_f32_e32 v208, s4, v220
	v_fmac_f32_e32 v208, s5, v221
	v_fmac_f32_e32 v209, s26, v220
	v_fmac_f32_e32 v209, s27, v221
	v_fmac_f32_e32 v210, s44, v220
	v_fmac_f32_e32 v210, s45, v221
	v_fmac_f32_e32 v211, s46, v220
	v_fmac_f32_e32 v211, s47, v221
	v_readlane_b32 s4, v188, s30
	v_readlane_b32 s5, v189, s30
	v_readlane_b32 s26, v191, s30
	v_readlane_b32 s27, v192, s30
	v_readlane_b32 s44, v194, s30
	v_readlane_b32 s45, v195, s30
	v_readlane_b32 s46, v197, s30
	v_readlane_b32 s47, v198, s30
	v_fmac_f32_e32 v212, s4, v220
	v_fmac_f32_e32 v212, s5, v221
	v_fmac_f32_e32 v213, s26, v220
	v_fmac_f32_e32 v213, s27, v221
	v_fmac_f32_e32 v214, s44, v220
	v_fmac_f32_e32 v214, s45, v221
	v_fmac_f32_e32 v215, s46, v220
	v_fmac_f32_e32 v215, s47, v221
	s_add_i32 s30, s17, 3
	s_nop 0
	v_readlane_b32 s4, v176, s30
	v_readlane_b32 s5, v177, s30
	v_readlane_b32 s26, v179, s30
	v_readlane_b32 s27, v180, s30
	v_readlane_b32 s44, v182, s30
	v_readlane_b32 s45, v183, s30
	v_readlane_b32 s46, v185, s30
	v_readlane_b32 s47, v186, s30
	v_fmac_f32_e32 v208, s4, v222
	v_fmac_f32_e32 v208, s5, v223
	v_fmac_f32_e32 v209, s26, v222
	v_fmac_f32_e32 v209, s27, v223
	v_fmac_f32_e32 v210, s44, v222
	v_fmac_f32_e32 v210, s45, v223
	v_fmac_f32_e32 v211, s46, v222
	v_fmac_f32_e32 v211, s47, v223
	v_readlane_b32 s4, v188, s30
	v_readlane_b32 s5, v189, s30
	v_readlane_b32 s26, v191, s30
	v_readlane_b32 s27, v192, s30
	v_readlane_b32 s44, v194, s30
	v_readlane_b32 s45, v195, s30
	v_readlane_b32 s46, v197, s30
	v_readlane_b32 s47, v198, s30
	v_fmac_f32_e32 v212, s4, v222
	v_fmac_f32_e32 v212, s5, v223
	v_fmac_f32_e32 v213, s26, v222
	v_fmac_f32_e32 v213, s27, v223
	v_fmac_f32_e32 v214, s44, v222
	v_fmac_f32_e32 v214, s45, v223
	v_fmac_f32_e32 v215, s46, v222
	v_fmac_f32_e32 v215, s47, v223
	v_add_u32_e32 v35, 0x800, v35
	ds_read2st64_b32 v[216:217], v35 offset0:0 offset1:64
	ds_read2st64_b32 v[218:219], v35 offset0:1 offset1:65
	ds_read2st64_b32 v[220:221], v35 offset0:2 offset1:66
	ds_read2st64_b32 v[222:223], v35 offset0:3 offset1:67
	s_waitcnt lgkmcnt(4)
	s_add_i32 s30, s17, 4
	s_nop 0
	v_readlane_b32 s4, v176, s30
	v_readlane_b32 s5, v177, s30
	v_readlane_b32 s26, v179, s30
	v_readlane_b32 s27, v180, s30
	v_readlane_b32 s44, v182, s30
	v_readlane_b32 s45, v183, s30
	v_readlane_b32 s46, v185, s30
	v_readlane_b32 s47, v186, s30
	v_fmac_f32_e32 v208, s4, v224
	v_fmac_f32_e32 v208, s5, v225
	v_fmac_f32_e32 v209, s26, v224
	v_fmac_f32_e32 v209, s27, v225
	v_fmac_f32_e32 v210, s44, v224
	v_fmac_f32_e32 v210, s45, v225
	v_fmac_f32_e32 v211, s46, v224
	v_fmac_f32_e32 v211, s47, v225
	v_readlane_b32 s4, v188, s30
	v_readlane_b32 s5, v189, s30
	v_readlane_b32 s26, v191, s30
	v_readlane_b32 s27, v192, s30
	v_readlane_b32 s44, v194, s30
	v_readlane_b32 s45, v195, s30
	v_readlane_b32 s46, v197, s30
	v_readlane_b32 s47, v198, s30
	v_fmac_f32_e32 v212, s4, v224
	v_fmac_f32_e32 v212, s5, v225
	v_fmac_f32_e32 v213, s26, v224
	v_fmac_f32_e32 v213, s27, v225
	v_fmac_f32_e32 v214, s44, v224
	v_fmac_f32_e32 v214, s45, v225
	v_fmac_f32_e32 v215, s46, v224
	v_fmac_f32_e32 v215, s47, v225
	s_add_i32 s30, s17, 5
	s_nop 0
	v_readlane_b32 s4, v176, s30
	v_readlane_b32 s5, v177, s30
	v_readlane_b32 s26, v179, s30
	v_readlane_b32 s27, v180, s30
	v_readlane_b32 s44, v182, s30
	v_readlane_b32 s45, v183, s30
	v_readlane_b32 s46, v185, s30
	v_readlane_b32 s47, v186, s30
	v_fmac_f32_e32 v208, s4, v226
	v_fmac_f32_e32 v208, s5, v227
	v_fmac_f32_e32 v209, s26, v226
	v_fmac_f32_e32 v209, s27, v227
	v_fmac_f32_e32 v210, s44, v226
	v_fmac_f32_e32 v210, s45, v227
	v_fmac_f32_e32 v211, s46, v226
	v_fmac_f32_e32 v211, s47, v227
	v_readlane_b32 s4, v188, s30
	v_readlane_b32 s5, v189, s30
	v_readlane_b32 s26, v191, s30
	v_readlane_b32 s27, v192, s30
	v_readlane_b32 s44, v194, s30
	v_readlane_b32 s45, v195, s30
	v_readlane_b32 s46, v197, s30
	v_readlane_b32 s47, v198, s30
	v_fmac_f32_e32 v212, s4, v226
	v_fmac_f32_e32 v212, s5, v227
	v_fmac_f32_e32 v213, s26, v226
	v_fmac_f32_e32 v213, s27, v227
	v_fmac_f32_e32 v214, s44, v226
	v_fmac_f32_e32 v214, s45, v227
	v_fmac_f32_e32 v215, s46, v226
	v_fmac_f32_e32 v215, s47, v227
	s_add_i32 s30, s17, 6
	s_nop 0
	v_readlane_b32 s4, v176, s30
	v_readlane_b32 s5, v177, s30
	v_readlane_b32 s26, v179, s30
	v_readlane_b32 s27, v180, s30
	v_readlane_b32 s44, v182, s30
	v_readlane_b32 s45, v183, s30
	v_readlane_b32 s46, v185, s30
	v_readlane_b32 s47, v186, s30
	v_fmac_f32_e32 v208, s4, v228
	v_fmac_f32_e32 v208, s5, v229
	v_fmac_f32_e32 v209, s26, v228
	v_fmac_f32_e32 v209, s27, v229
	v_fmac_f32_e32 v210, s44, v228
	v_fmac_f32_e32 v210, s45, v229
	v_fmac_f32_e32 v211, s46, v228
	v_fmac_f32_e32 v211, s47, v229
	v_readlane_b32 s4, v188, s30
	v_readlane_b32 s5, v189, s30
	v_readlane_b32 s26, v191, s30
	v_readlane_b32 s27, v192, s30
	v_readlane_b32 s44, v194, s30
	v_readlane_b32 s45, v195, s30
	v_readlane_b32 s46, v197, s30
	v_readlane_b32 s47, v198, s30
	v_fmac_f32_e32 v212, s4, v228
	v_fmac_f32_e32 v212, s5, v229
	v_fmac_f32_e32 v213, s26, v228
	v_fmac_f32_e32 v213, s27, v229
	v_fmac_f32_e32 v214, s44, v228
	v_fmac_f32_e32 v214, s45, v229
	v_fmac_f32_e32 v215, s46, v228
	v_fmac_f32_e32 v215, s47, v229
	s_add_i32 s30, s17, 7
	s_nop 0
	v_readlane_b32 s4, v176, s30
	v_readlane_b32 s5, v177, s30
	v_readlane_b32 s26, v179, s30
	v_readlane_b32 s27, v180, s30
	v_readlane_b32 s44, v182, s30
	v_readlane_b32 s45, v183, s30
	v_readlane_b32 s46, v185, s30
	v_readlane_b32 s47, v186, s30
	v_fmac_f32_e32 v208, s4, v230
	v_fmac_f32_e32 v208, s5, v231
	v_fmac_f32_e32 v209, s26, v230
	v_fmac_f32_e32 v209, s27, v231
	v_fmac_f32_e32 v210, s44, v230
	v_fmac_f32_e32 v210, s45, v231
	v_fmac_f32_e32 v211, s46, v230
	v_fmac_f32_e32 v211, s47, v231
	v_readlane_b32 s4, v188, s30
	v_readlane_b32 s5, v189, s30
	v_readlane_b32 s26, v191, s30
	v_readlane_b32 s27, v192, s30
	v_readlane_b32 s44, v194, s30
	v_readlane_b32 s45, v195, s30
	v_readlane_b32 s46, v197, s30
	v_readlane_b32 s47, v198, s30
	v_fmac_f32_e32 v212, s4, v230
	v_fmac_f32_e32 v212, s5, v231
	v_fmac_f32_e32 v213, s26, v230
	v_fmac_f32_e32 v213, s27, v231
	v_fmac_f32_e32 v214, s44, v230
	v_fmac_f32_e32 v214, s45, v231
	v_fmac_f32_e32 v215, s46, v230
	v_fmac_f32_e32 v215, s47, v231
	s_add_i32 s17, s17, 8
	s_cmp_lt_u32 s17, 64
	s_cbranch_scc1 .Lsm_pv
	s_waitcnt lgkmcnt(0)
	v_readlane_b32 s4, v178, 0
	v_readlane_b32 s5, v178, 1
	v_readlane_b32 s26, v178, 2
	v_readlane_b32 s27, v178, 3
	v_readlane_b32 s44, v178, 4
	v_readlane_b32 s45, v178, 5
	v_readlane_b32 s46, v178, 6
	v_readlane_b32 s47, v178, 7
	v_fmac_f32_e32 v208, s4, v0
	v_fmac_f32_e32 v208, s5, v1
	v_fmac_f32_e32 v208, s26, v2
	v_fmac_f32_e32 v208, s27, v3
	v_fmac_f32_e32 v208, s44, v4
	v_fmac_f32_e32 v208, s45, v5
	v_fmac_f32_e32 v208, s46, v6
	v_fmac_f32_e32 v208, s47, v7
	v_readlane_b32 s4, v181, 0
	v_readlane_b32 s5, v181, 1
	v_readlane_b32 s26, v181, 2
	v_readlane_b32 s27, v181, 3
	v_readlane_b32 s44, v181, 4
	v_readlane_b32 s45, v181, 5
	v_readlane_b32 s46, v181, 6
	v_readlane_b32 s47, v181, 7
	v_fmac_f32_e32 v209, s4, v0
	v_fmac_f32_e32 v209, s5, v1
	v_fmac_f32_e32 v209, s26, v2
	v_fmac_f32_e32 v209, s27, v3
	v_fmac_f32_e32 v209, s44, v4
	v_fmac_f32_e32 v209, s45, v5
	v_fmac_f32_e32 v209, s46, v6
	v_fmac_f32_e32 v209, s47, v7
	v_readlane_b32 s4, v184, 0
	v_readlane_b32 s5, v184, 1
	v_readlane_b32 s26, v184, 2
	v_readlane_b32 s27, v184, 3
	v_readlane_b32 s44, v184, 4
	v_readlane_b32 s45, v184, 5
	v_readlane_b32 s46, v184, 6
	v_readlane_b32 s47, v184, 7
	v_fmac_f32_e32 v210, s4, v0
	v_fmac_f32_e32 v210, s5, v1
	v_fmac_f32_e32 v210, s26, v2
	v_fmac_f32_e32 v210, s27, v3
	v_fmac_f32_e32 v210, s44, v4
	v_fmac_f32_e32 v210, s45, v5
	v_fmac_f32_e32 v210, s46, v6
	v_fmac_f32_e32 v210, s47, v7
	v_readlane_b32 s4, v187, 0
	v_readlane_b32 s5, v187, 1
	v_readlane_b32 s26, v187, 2
	v_readlane_b32 s27, v187, 3
	v_readlane_b32 s44, v187, 4
	v_readlane_b32 s45, v187, 5
	v_readlane_b32 s46, v187, 6
	v_readlane_b32 s47, v187, 7
	v_fmac_f32_e32 v211, s4, v0
	v_fmac_f32_e32 v211, s5, v1
	v_fmac_f32_e32 v211, s26, v2
	v_fmac_f32_e32 v211, s27, v3
	v_fmac_f32_e32 v211, s44, v4
	v_fmac_f32_e32 v211, s45, v5
	v_fmac_f32_e32 v211, s46, v6
	v_fmac_f32_e32 v211, s47, v7
	v_readlane_b32 s4, v190, 0
	v_readlane_b32 s5, v190, 1
	v_readlane_b32 s26, v190, 2
	v_readlane_b32 s27, v190, 3
	v_readlane_b32 s44, v190, 4
	v_readlane_b32 s45, v190, 5
	v_readlane_b32 s46, v190, 6
	v_readlane_b32 s47, v190, 7
	v_fmac_f32_e32 v212, s4, v0
	v_fmac_f32_e32 v212, s5, v1
	v_fmac_f32_e32 v212, s26, v2
	v_fmac_f32_e32 v212, s27, v3
	v_fmac_f32_e32 v212, s44, v4
	v_fmac_f32_e32 v212, s45, v5
	v_fmac_f32_e32 v212, s46, v6
	v_fmac_f32_e32 v212, s47, v7
	v_readlane_b32 s4, v193, 0
	v_readlane_b32 s5, v193, 1
	v_readlane_b32 s26, v193, 2
	v_readlane_b32 s27, v193, 3
	v_readlane_b32 s44, v193, 4
	v_readlane_b32 s45, v193, 5
	v_readlane_b32 s46, v193, 6
	v_readlane_b32 s47, v193, 7
	v_fmac_f32_e32 v213, s4, v0
	v_fmac_f32_e32 v213, s5, v1
	v_fmac_f32_e32 v213, s26, v2
	v_fmac_f32_e32 v213, s27, v3
	v_fmac_f32_e32 v213, s44, v4
	v_fmac_f32_e32 v213, s45, v5
	v_fmac_f32_e32 v213, s46, v6
	v_fmac_f32_e32 v213, s47, v7
	v_readlane_b32 s4, v196, 0
	v_readlane_b32 s5, v196, 1
	v_readlane_b32 s26, v196, 2
	v_readlane_b32 s27, v196, 3
	v_readlane_b32 s44, v196, 4
	v_readlane_b32 s45, v196, 5
	v_readlane_b32 s46, v196, 6
	v_readlane_b32 s47, v196, 7
	v_fmac_f32_e32 v214, s4, v0
	v_fmac_f32_e32 v214, s5, v1
	v_fmac_f32_e32 v214, s26, v2
	v_fmac_f32_e32 v214, s27, v3
	v_fmac_f32_e32 v214, s44, v4
	v_fmac_f32_e32 v214, s45, v5
	v_fmac_f32_e32 v214, s46, v6
	v_fmac_f32_e32 v214, s47, v7
	v_readlane_b32 s4, v199, 0
	v_readlane_b32 s5, v199, 1
	v_readlane_b32 s26, v199, 2
	v_readlane_b32 s27, v199, 3
	v_readlane_b32 s44, v199, 4
	v_readlane_b32 s45, v199, 5
	v_readlane_b32 s46, v199, 6
	v_readlane_b32 s47, v199, 7
	v_fmac_f32_e32 v215, s4, v0
	v_fmac_f32_e32 v215, s5, v1
	v_fmac_f32_e32 v215, s26, v2
	v_fmac_f32_e32 v215, s27, v3
	v_fmac_f32_e32 v215, s44, v4
	v_fmac_f32_e32 v215, s45, v5
	v_fmac_f32_e32 v215, s46, v6
	v_fmac_f32_e32 v215, s47, v7
	v_div_scale_f32 v38, s[26:27], v200, v200, v208
	v_rcp_f32_e32 v39, v38
	s_add_i32 s26, s16, 0
	s_ashr_i32 s27, s26, 31
	v_fma_f32 v40, -v38, v39, 1.0
	v_fmac_f32_e32 v39, v40, v39
	v_div_scale_f32 v40, vcc, v208, v200, v208
	v_mul_f32_e32 v41, v40, v39
	v_fma_f32 v42, -v38, v41, v40
	v_fmac_f32_e32 v41, v42, v39
	v_fma_f32 v38, -v38, v41, v40
	v_div_fmas_f32 v38, v38, v39, v41
	v_div_fixup_f32 v38, v38, v200, v208
	s_lshl_b64 s[26:27], s[26:27], 11
	v_bfe_u32 v39, v38, 16, 1
	v_add3_u32 v39, v38, v39, s48
	v_lshl_add_u64 v[40:41], v[8:9], 0, s[26:27]
	flat_store_short_d16_hi v[40:41], v39
	v_div_scale_f32 v38, s[26:27], v201, v201, v209
	v_rcp_f32_e32 v39, v38
	s_add_i32 s26, s16, 1
	s_ashr_i32 s27, s26, 31
	v_fma_f32 v40, -v38, v39, 1.0
	v_fmac_f32_e32 v39, v40, v39
	v_div_scale_f32 v40, vcc, v209, v201, v209
	v_mul_f32_e32 v41, v40, v39
	v_fma_f32 v42, -v38, v41, v40
	v_fmac_f32_e32 v41, v42, v39
	v_fma_f32 v38, -v38, v41, v40
	v_div_fmas_f32 v38, v38, v39, v41
	v_div_fixup_f32 v38, v38, v201, v209
	s_lshl_b64 s[26:27], s[26:27], 11
	v_bfe_u32 v39, v38, 16, 1
	v_add3_u32 v39, v38, v39, s48
	v_lshl_add_u64 v[40:41], v[8:9], 0, s[26:27]
	flat_store_short_d16_hi v[40:41], v39
	v_div_scale_f32 v38, s[26:27], v202, v202, v210
	v_rcp_f32_e32 v39, v38
	s_add_i32 s26, s16, 2
	s_ashr_i32 s27, s26, 31
	v_fma_f32 v40, -v38, v39, 1.0
	v_fmac_f32_e32 v39, v40, v39
	v_div_scale_f32 v40, vcc, v210, v202, v210
	v_mul_f32_e32 v41, v40, v39
	v_fma_f32 v42, -v38, v41, v40
	v_fmac_f32_e32 v41, v42, v39
	v_fma_f32 v38, -v38, v41, v40
	v_div_fmas_f32 v38, v38, v39, v41
	v_div_fixup_f32 v38, v38, v202, v210
	s_lshl_b64 s[26:27], s[26:27], 11
	v_bfe_u32 v39, v38, 16, 1
	v_add3_u32 v39, v38, v39, s48
	v_lshl_add_u64 v[40:41], v[8:9], 0, s[26:27]
	flat_store_short_d16_hi v[40:41], v39
	v_div_scale_f32 v38, s[26:27], v203, v203, v211
	v_rcp_f32_e32 v39, v38
	s_add_i32 s26, s16, 3
	s_ashr_i32 s27, s26, 31
	v_fma_f32 v40, -v38, v39, 1.0
	v_fmac_f32_e32 v39, v40, v39
	v_div_scale_f32 v40, vcc, v211, v203, v211
	v_mul_f32_e32 v41, v40, v39
	v_fma_f32 v42, -v38, v41, v40
	v_fmac_f32_e32 v41, v42, v39
	v_fma_f32 v38, -v38, v41, v40
	v_div_fmas_f32 v38, v38, v39, v41
	v_div_fixup_f32 v38, v38, v203, v211
	s_lshl_b64 s[26:27], s[26:27], 11
	v_bfe_u32 v39, v38, 16, 1
	v_add3_u32 v39, v38, v39, s48
	v_lshl_add_u64 v[40:41], v[8:9], 0, s[26:27]
	flat_store_short_d16_hi v[40:41], v39
	v_div_scale_f32 v38, s[26:27], v204, v204, v212
	v_rcp_f32_e32 v39, v38
	s_add_i32 s26, s16, 4
	s_ashr_i32 s27, s26, 31
	v_fma_f32 v40, -v38, v39, 1.0
	v_fmac_f32_e32 v39, v40, v39
	v_div_scale_f32 v40, vcc, v212, v204, v212
	v_mul_f32_e32 v41, v40, v39
	v_fma_f32 v42, -v38, v41, v40
	v_fmac_f32_e32 v41, v42, v39
	v_fma_f32 v38, -v38, v41, v40
	v_div_fmas_f32 v38, v38, v39, v41
	v_div_fixup_f32 v38, v38, v204, v212
	s_lshl_b64 s[26:27], s[26:27], 11
	v_bfe_u32 v39, v38, 16, 1
	v_add3_u32 v39, v38, v39, s48
	v_lshl_add_u64 v[40:41], v[8:9], 0, s[26:27]
	flat_store_short_d16_hi v[40:41], v39
	v_div_scale_f32 v38, s[26:27], v205, v205, v213
	v_rcp_f32_e32 v39, v38
	s_add_i32 s26, s16, 5
	s_ashr_i32 s27, s26, 31
	v_fma_f32 v40, -v38, v39, 1.0
	v_fmac_f32_e32 v39, v40, v39
	v_div_scale_f32 v40, vcc, v213, v205, v213
	v_mul_f32_e32 v41, v40, v39
	v_fma_f32 v42, -v38, v41, v40
	v_fmac_f32_e32 v41, v42, v39
	v_fma_f32 v38, -v38, v41, v40
	v_div_fmas_f32 v38, v38, v39, v41
	v_div_fixup_f32 v38, v38, v205, v213
	s_lshl_b64 s[26:27], s[26:27], 11
	v_bfe_u32 v39, v38, 16, 1
	v_add3_u32 v39, v38, v39, s48
	v_lshl_add_u64 v[40:41], v[8:9], 0, s[26:27]
	flat_store_short_d16_hi v[40:41], v39
	v_div_scale_f32 v38, s[26:27], v206, v206, v214
	v_rcp_f32_e32 v39, v38
	s_add_i32 s26, s16, 6
	s_ashr_i32 s27, s26, 31
	v_fma_f32 v40, -v38, v39, 1.0
	v_fmac_f32_e32 v39, v40, v39
	v_div_scale_f32 v40, vcc, v214, v206, v214
	v_mul_f32_e32 v41, v40, v39
	v_fma_f32 v42, -v38, v41, v40
	v_fmac_f32_e32 v41, v42, v39
	v_fma_f32 v38, -v38, v41, v40
	v_div_fmas_f32 v38, v38, v39, v41
	v_div_fixup_f32 v38, v38, v206, v214
	s_lshl_b64 s[26:27], s[26:27], 11
	v_bfe_u32 v39, v38, 16, 1
	v_add3_u32 v39, v38, v39, s48
	v_lshl_add_u64 v[40:41], v[8:9], 0, s[26:27]
	flat_store_short_d16_hi v[40:41], v39
	v_div_scale_f32 v38, s[26:27], v207, v207, v215
	v_rcp_f32_e32 v39, v38
	s_add_i32 s26, s16, 7
	s_ashr_i32 s27, s26, 31
	v_fma_f32 v40, -v38, v39, 1.0
	v_fmac_f32_e32 v39, v40, v39
	v_div_scale_f32 v40, vcc, v215, v207, v215
	v_mul_f32_e32 v41, v40, v39
	v_fma_f32 v42, -v38, v41, v40
	v_fmac_f32_e32 v41, v42, v39
	v_fma_f32 v38, -v38, v41, v40
	v_div_fmas_f32 v38, v38, v39, v41
	v_div_fixup_f32 v38, v38, v207, v215
	s_lshl_b64 s[26:27], s[26:27], 11
	v_bfe_u32 v39, v38, 16, 1
	v_add3_u32 v39, v38, v39, s48
	v_lshl_add_u64 v[40:41], v[8:9], 0, s[26:27]
	flat_store_short_d16_hi v[40:41], v39
	s_add_i32 s15, s15, s74
	s_cmpk_gt_i32 s15, 0xff
	s_waitcnt lgkmcnt(0)
	s_barrier
	s_cbranch_scc0 .LBB0_689
